# attention fast loop cleanup: dead readfirstlanes / exit moves removed, V-store LDS base hoisted, back-to-back vmcnt waits merged
# baseline (speedup 1.0000x reference)
.LBB0_448:
	s_or_b64 exec, exec, s[34:35]
	s_xor_b64 s[34:35], s[20:21], -1
	s_and_b64 s[20:21], s[20:21], exec
	v_add_u32_e32 v6, 0x200, v2
	v_add_u32_e32 v14, 0x400, v2
	v_add_u32_e32 v16, 0x600, v2
	s_cselect_b32 s20, s63, s64
	v_ashrrev_i32_e32 v23, 4, v2
	v_ashrrev_i32_e32 v28, 4, v6
	v_ashrrev_i32_e32 v30, 4, v14
	v_ashrrev_i32_e32 v32, 4, v16
	s_lshl_b32 s38, s20, 7
	v_min_i32_e32 v4, 0x7f, v23
	v_min_i32_e32 v6, 0x7f, v28
	v_min_i32_e32 v14, 0x7f, v30
	v_min_i32_e32 v16, 0x7f, v32
	v_lshlrev_b32_e32 v0, 4, v2
	v_add_u32_e32 v4, s38, v4
	v_add_u32_e32 v6, s38, v6
	v_add_u32_e32 v14, s38, v14
	v_add_u32_e32 v16, s38, v16
	v_and_b32_e32 v0, 0xf0, v0
	v_ashrrev_i32_e32 v5, 31, v4
	v_ashrrev_i32_e32 v7, 31, v6
	v_ashrrev_i32_e32 v15, 31, v14
	v_ashrrev_i32_e32 v17, 31, v16
	v_lshl_add_u64 v[12:13], s[10:11], 0, v[0:1]
	v_lshlrev_b64 v[4:5], 11, v[4:5]
	v_lshlrev_b64 v[6:7], 11, v[6:7]
	v_lshlrev_b64 v[14:15], 11, v[14:15]
	v_lshlrev_b64 v[16:17], 11, v[16:17]
	v_lshl_add_u64 v[4:5], v[12:13], 0, v[4:5]
	v_lshl_add_u64 v[8:9], v[12:13], 0, v[6:7]
	v_lshl_add_u64 v[14:15], v[12:13], 0, v[14:15]
	v_lshl_add_u64 v[16:17], v[12:13], 0, v[16:17]
	global_load_dwordx4 v[4:7], v[4:5], off
	s_nop 0
	global_load_dwordx4 v[8:11], v[8:9], off
	s_nop 0
	global_load_dwordx4 v[12:15], v[14:15], off
	s_nop 0
	global_load_dwordx4 v[16:19], v[16:17], off
	v_ashrrev_i32_e32 v20, 3, v2
	v_ashrrev_i32_e32 v21, 31, v20
	v_lshlrev_b32_e32 v26, 5, v2
	s_add_i32 s20, 0, 0x11000
	v_lshlrev_b64 v[24:25], 11, v[20:21]
	v_add_u32_e32 v22, s20, v0
	v_and_b32_e32 v0, 0xe0, v26
	v_lshl_add_u64 v[24:25], s[12:13], 0, v[24:25]
	v_mad_u64_u32 v[26:27], s[20:21], v23, s51, v[22:23]
	v_lshl_add_u64 v[24:25], v[24:25], 0, v[0:1]
	v_mad_u64_u32 v[28:29], s[20:21], v28, s51, v[22:23]
	v_mad_u64_u32 v[30:31], s[20:21], v30, s51, v[22:23]
	v_mad_u64_u32 v[22:23], s[20:21], v32, s51, v[22:23]
	v_lshlrev_b32_e32 v3, 4, v3
	v_and_b32_e32 v165, 31, v2
	s_lshl_b32 s39, s65, 5
	s_ashr_i32 s40, s65, 2
	s_and_b32 s20, s39, 0x60
	v_or_b32_e32 v174, s20, v165
	s_lshl_b32 s41, s40, 7
	s_or_b32 s21, s38, 0x7f
	v_mov_b32_e32 v79, 0
	s_cmpk_lt_i32 s21, 0xffc1
	v_mov_b32_e32 v78, 0
	v_mov_b32_e32 v77, 0
	v_mov_b32_e32 v76, 0
	v_mov_b32_e32 v75, 0
	v_mov_b32_e32 v74, 0
	v_mov_b32_e32 v73, 0
	v_mov_b32_e32 v72, 0
	v_mov_b32_e32 v71, 0
	v_mov_b32_e32 v70, 0
	v_mov_b32_e32 v69, 0
	v_mov_b32_e32 v68, 0
	v_mov_b32_e32 v67, 0
	v_mov_b32_e32 v66, 0
	v_mov_b32_e32 v65, 0
	v_mov_b32_e32 v64, v79
	v_mov_b32_e32 v63, 0
	v_mov_b32_e32 v62, 0
	v_mov_b32_e32 v61, 0
	v_mov_b32_e32 v60, 0
	v_mov_b32_e32 v59, 0
	v_mov_b32_e32 v58, 0
	v_mov_b32_e32 v57, 0
	v_mov_b32_e32 v56, 0
	v_mov_b32_e32 v55, 0
	v_mov_b32_e32 v54, 0
	s_waitcnt vmcnt(3)
	ds_write_b128 v26, v[4:7]
	s_waitcnt vmcnt(2)
	ds_write_b128 v28, v[8:11]
	s_waitcnt vmcnt(1)
	ds_write_b128 v30, v[12:15]
	s_waitcnt vmcnt(0)
	ds_write_b128 v22, v[16:19]
	global_load_dwordx4 v[4:7], v[24:25], off
	global_load_dwordx4 v[8:11], v[24:25], off offset:16
	v_bfe_u32 v12, v2, 2, 4
	v_ashrrev_i32_e32 v14, 5, v2
	v_and_or_b32 v3, v3, 16, v12
	v_bfi_b32 v16, -4, v14, v2
	v_mov_b32_e32 v13, v1
	v_mul_lo_u32 v15, v20, s51
	v_lshlrev_b32_e32 v12, 12, v3
	v_lshlrev_b32_e32 v14, 3, v16
	v_add_u32_e32 v17, 0, v15
	v_lshl_add_u64 v[12:13], s[14:15], 0, v[12:13]
	v_ashrrev_i32_e32 v15, 31, v14
	v_add_u32_e32 v176, v17, v0
	v_lshl_add_u64 v[12:13], v[14:15], 1, v[12:13]
	v_bfe_u32 v0, v2, 5, 1
	v_mul_lo_u32 v2, v16, s56
	v_lshlrev_b32_e32 v3, 2, v3
	v_add_u32_e32 v2, 0, v2
	v_add_u32_e32 v177, v2, v3
	v_add_u32_e32 v178, 0x8800, v177
	v_lshl_add_u64 v[166:167], v[24:25], 0, s[4:5]
	v_lshlrev_b32_e32 v173, 4, v0
	v_lshlrev_b32_e32 v164, 3, v0
	v_mov_b32_e32 v53, 0
	v_mov_b32_e32 v52, 0
	v_mov_b32_e32 v51, 0
	v_mov_b32_e32 v50, 0
	v_mov_b32_e32 v49, 0
	v_mov_b32_e32 v48, v79
	v_mov_b32_e32 v47, 0
	v_mov_b32_e32 v46, 0
	v_mov_b32_e32 v45, 0
	v_mov_b32_e32 v44, 0
	v_mov_b32_e32 v43, 0
	v_mov_b32_e32 v42, 0
	v_mov_b32_e32 v41, 0
	v_mov_b32_e32 v40, 0
	v_mov_b32_e32 v39, 0
	v_mov_b32_e32 v38, 0
	v_mov_b32_e32 v37, 0
	v_mov_b32_e32 v36, 0
	v_mov_b32_e32 v35, 0
	v_mov_b32_e32 v34, 0
	v_mov_b32_e32 v33, 0
	v_mov_b32_e32 v32, v79
	v_mov_b32_e32 v31, 0
	v_mov_b32_e32 v30, 0
	v_mov_b32_e32 v29, 0
	v_mov_b32_e32 v28, 0
	v_mov_b32_e32 v27, 0
	v_mov_b32_e32 v26, 0
	v_mov_b32_e32 v25, 0
	s_waitcnt vmcnt(1)
	ds_write_b128 v176, v[4:7]
	s_waitcnt vmcnt(0)
	ds_write_b128 v176, v[8:11] offset:16
	global_load_dwordx4 v[4:7], v[12:13], off
	global_load_dwordx4 v[8:11], v[12:13], off offset:2048
	v_lshl_add_u64 v[168:169], v[12:13], 0, s[4:5]
	v_mov_b32_e32 v24, 0
	v_mov_b32_e32 v23, 0
	v_mov_b32_e32 v22, 0
	v_mov_b32_e32 v21, 0
	v_mov_b32_e32 v20, 0
	v_mov_b32_e32 v19, 0
	v_mov_b32_e32 v18, 0
	v_mov_b32_e32 v17, 0
	v_mov_b32_e32 v16, v79
	v_mov_b32_e32 v175, 0
	s_waitcnt vmcnt(1)
	v_and_b32_e32 v2, 0xffff, v4
	v_lshrrev_b32_e32 v3, 16, v4
	v_and_b32_e32 v4, 0xffff, v5
	v_lshrrev_b32_e32 v5, 16, v5
	v_and_b32_e32 v12, 0xffff, v6
	v_lshrrev_b32_e32 v6, 16, v6
	v_and_b32_e32 v13, 0xffff, v7
	v_lshrrev_b32_e32 v7, 16, v7
	s_waitcnt vmcnt(0)
	v_lshl_or_b32 v2, v8, 16, v2
	v_and_or_b32 v3, v8, s57, v3
	v_lshl_or_b32 v4, v9, 16, v4
	v_and_or_b32 v5, v9, s57, v5
	v_lshl_or_b32 v8, v10, 16, v12
	v_and_or_b32 v6, v10, s57, v6
	v_lshl_or_b32 v9, v11, 16, v13
	v_and_or_b32 v7, v11, s57, v7
	ds_write2_b32 v178, v2, v3 offset1:34
	ds_write2_b32 v178, v4, v5 offset0:68 offset1:102
	ds_write2_b32 v178, v8, v6 offset0:136 offset1:170
	ds_write2_b32 v178, v9, v7 offset0:204 offset1:238
	global_load_dwordx4 v[120:123], v[166:167], off offset:16
	global_load_dwordx4 v[124:127], v[166:167], off
	global_load_dwordx4 v[116:119], v[168:169], off
	global_load_dwordx4 v[112:115], v[168:169], off offset:2048
	v_mul_u32_u24_e32 v2, 0x110, v174
	v_or_b32_e32 v3, s41, v173
	v_add3_u32 v179, v3, v2, s50
	v_mul_u32_u24_e32 v2, 0x88, v165
	v_mul_u32_u24_e32 v3, 0x110, v165
	v_add3_u32 v2, v2, v164, s58
	v_add3_u32 v180, v173, v3, s41
	s_waitcnt lgkmcnt(0)
	s_barrier
	s_cbranch_scc1 .LBB0_465
	s_ashr_i32 s41, s21, 31
	v_lshlrev_b32_e32 v0, 2, v0
	s_lshr_b32 s41, s41, 26
	v_sub_u32_e32 v0, v0, v165
	s_add_i32 s21, s21, s41
	v_subrev_u32_e32 v0, s20, v0
	v_mov_b32_e32 v14, v1
	v_mov_b32_e32 v15, v1
	s_ashr_i32 s21, s21, 6
	s_or_b32 s42, s20, s38
	v_add_u32_e32 v181, 0, v2
	v_subrev_u32_e32 v182, s38, v0
	v_mov_b32_e32 v0, v1
	v_mov_b32_e32 v2, v1
	v_mov_b32_e32 v3, v1
	v_mov_b32_e32 v4, v1
	v_mov_b32_e32 v5, v1
	v_mov_b32_e32 v6, v1
	v_mov_b32_e32 v7, v1
	v_mov_b32_e32 v8, v1
	v_mov_b32_e32 v9, v1
	v_mov_b32_e32 v10, v1
	v_mov_b32_e32 v11, v1
	v_mov_b32_e32 v12, v1
	v_mov_b32_e32 v13, v1
	v_mov_b64_e32 v[30:31], v[14:15]
	v_mov_b64_e32 v[46:47], v[14:15]
	v_mov_b64_e32 v[62:63], v[14:15]
	v_mov_b64_e32 v[78:79], v[14:15]
	s_min_i32 s41, s21, 0xff
	s_ashr_i32 s43, s42, 6
	s_mov_b32 s44, 0
	v_mov_b32_e32 v175, 0
	s_movk_i32 s45, 0xda
	v_mov_b64_e32 v[28:29], v[12:13]
	v_mov_b64_e32 v[26:27], v[10:11]
	v_mov_b64_e32 v[24:25], v[8:9]
	v_mov_b64_e32 v[22:23], v[6:7]
	v_mov_b64_e32 v[20:21], v[4:5]
	v_mov_b64_e32 v[18:19], v[2:3]
	v_mov_b64_e32 v[16:17], v[0:1]
	v_mov_b64_e32 v[44:45], v[12:13]
	v_mov_b64_e32 v[42:43], v[10:11]
	v_mov_b64_e32 v[40:41], v[8:9]
	v_mov_b64_e32 v[38:39], v[6:7]
	v_mov_b64_e32 v[36:37], v[4:5]
	v_mov_b64_e32 v[34:35], v[2:3]
	v_mov_b64_e32 v[32:33], v[0:1]
	v_mov_b64_e32 v[60:61], v[12:13]
	v_mov_b64_e32 v[58:59], v[10:11]
	v_mov_b64_e32 v[56:57], v[8:9]
	v_mov_b64_e32 v[54:55], v[6:7]
	v_mov_b64_e32 v[52:53], v[4:5]
	v_mov_b64_e32 v[50:51], v[2:3]
	v_mov_b64_e32 v[48:49], v[0:1]
	v_mov_b64_e32 v[76:77], v[12:13]
	v_mov_b64_e32 v[74:75], v[10:11]
	v_mov_b64_e32 v[72:73], v[8:9]
	v_mov_b64_e32 v[70:71], v[6:7]
	v_mov_b64_e32 v[68:69], v[4:5]
	v_mov_b64_e32 v[66:67], v[2:3]
	v_mov_b64_e32 v[64:65], v[0:1]
	v_cmp_gt_f32_e32 vcc, 0xc2700000, v171
	s_cbranch_vccnz .LBB0_451
	s_mov_b32 s100, 0x05040100
	s_mov_b32 s101, 0x07060302
	ds_read_b128 v[234:237], v179
	ds_read_b128 v[238:241], v179 offset:32
	ds_read_b128 v[244:247], v179 offset:64
	ds_read_b128 v[248:251], v179 offset:96
	s_waitcnt lgkmcnt(0)
	v_readfirstlane_b32 s86, v166
	v_readfirstlane_b32 s87, v167
	v_readfirstlane_b32 s88, v168
	v_readfirstlane_b32 s89, v169
	v_subrev_u32_e32 v252, s86, v166
	v_subrev_u32_e32 v253, s88, v168
	v_add_u32_e32 v254, 0xcc00, v177
	s_branch .Lqf_451

.Lqf_450:
	s_and_b64 vcc, exec, s[20:21]
	s_cbranch_vccnz .LBB0_465

.Lqf_457:
	s_waitcnt vmcnt(4)
	v_perm_b32 v0, v112, v116, s100
	v_perm_b32 v80, v112, v116, s101
	ds_write2_b32 v254, v0, v80 offset1:34
	v_perm_b32 v0, v113, v117, s100
	v_perm_b32 v80, v113, v117, s101
	ds_write2_b32 v254, v0, v80 offset0:68 offset1:102
	v_perm_b32 v0, v114, v118, s100
	v_perm_b32 v80, v114, v118, s101
	ds_write2_b32 v254, v0, v80 offset0:136 offset1:170
	v_perm_b32 v0, v115, v119, s100
	v_perm_b32 v80, v115, v119, s101
	s_mov_b64 s[20:21], -1
	s_cmp_ge_i32 s44, s41
	ds_write2_b32 v254, v0, v80 offset0:204 offset1:238
	s_waitcnt lgkmcnt(0)
	s_barrier
	s_cbranch_scc1 .Lqf_450
	s_add_u32 s86, s86, s4
	s_addc_u32 s87, s87, s5
	s_add_u32 s88, s88, s4
	s_addc_u32 s89, s89, s5
	global_load_dwordx4 v[120:123], v252, s[86:87] offset:16
	global_load_dwordx4 v[124:127], v252, s[86:87]
	global_load_dwordx4 v[116:119], v253, s[88:89]
	global_load_dwordx4 v[112:115], v253, s[88:89] offset:2048
	s_cmp_lt_i32 s44, s43
	s_cselect_b64 s[20:21], -1, 0
	s_cmp_ge_i32 s44, s43
	s_cbranch_scc1 .Lqf_462
	ds_read_b128 v[80:83], v180 offset:17408
	ds_read_b128 v[152:155], v180 offset:17440
	ds_read_b128 v[100:103], v180 offset:26112
	ds_read_b128 v[156:159], v180 offset:26144
	s_cmp_le_i32 s45, s42
	s_waitcnt lgkmcnt(3)
	v_mfma_f32_32x32x16_bf16 v[80:95], v[80:83], v[234:237], 0
	s_waitcnt lgkmcnt(1)
	v_mfma_f32_32x32x16_bf16 v[96:111], v[100:103], v[234:237], 0
	s_waitcnt lgkmcnt(2)
	v_mfma_f32_32x32x16_bf16 v[80:95], v[152:155], v[238:241], v[80:95]
	s_waitcnt lgkmcnt(0)
	v_mfma_f32_32x32x16_bf16 v[96:111], v[156:159], v[238:241], v[96:111]
	ds_read_b128 v[148:151], v180 offset:17472
	ds_read_b128 v[160:163], v180 offset:17504
	s_waitcnt lgkmcnt(1)
	v_mfma_f32_32x32x16_bf16 v[80:95], v[148:151], v[244:247], v[80:95]
	ds_read_b128 v[148:151], v180 offset:26176
	ds_read_b128 v[184:187], v180 offset:26208
	s_waitcnt lgkmcnt(1)
	v_mfma_f32_32x32x16_bf16 v[96:111], v[148:151], v[244:247], v[96:111]
	s_waitcnt lgkmcnt(2)
	v_mfma_f32_32x32x16_bf16 v[80:95], v[160:163], v[248:251], v[80:95]
	s_waitcnt lgkmcnt(0)
	v_mfma_f32_32x32x16_bf16 v[96:111], v[184:187], v[248:251], v[96:111]
	s_cbranch_scc1 .Lqf_461
	v_add_u32_e32 v0, s45, v182
	v_add_u32_e32 v148, 0xffffff67, v0
	s_add_i32 s68, 0, 0x19800
	v_max_i32_e32 v148, 0xffffff80, v148
	v_lshl_add_u32 v150, v148, 2, s68
	v_add_u32_e32 v148, 0xffffff68, v0
	v_add_u32_e32 v14, 0xffffff66, v0
	v_add_u32_e32 v15, 0xffffff86, v0
	v_add_u32_e32 v149, 0xffffff87, v0
	v_add_u32_e32 v151, 0xffffff88, v0
	v_max_i32_e32 v148, 0xffffff80, v148
	v_add_u32_e32 v153, 0xffffff89, v0
	v_max_i32_e32 v14, 0xffffff80, v14
	v_max_i32_e32 v15, 0xffffff80, v15
	v_max_i32_e32 v149, 0xffffff80, v149
	v_max_i32_e32 v151, 0xffffff80, v151
	v_lshl_add_u32 v152, v148, 2, s68
	v_add_u32_e32 v148, 0xffffff69, v0
	v_max_i32_e32 v153, 0xffffff80, v153
	v_lshl_add_u32 v14, v14, 2, s68
	v_lshl_add_u32 v15, v15, 2, s68
	v_lshl_add_u32 v149, v149, 2, s68
	v_lshl_add_u32 v151, v151, 2, s68
	v_max_i32_e32 v148, 0xffffff80, v148
	v_lshl_add_u32 v153, v153, 2, s68
	v_lshl_add_u32 v154, v148, 2, s68
	ds_read_b32 v14, v14 offset:512
	ds_read_b32 v148, v15 offset:512
	ds_read_b32 v15, v150 offset:512
	ds_read_b32 v149, v149 offset:512
	ds_read_b32 v150, v152 offset:512
	ds_read_b32 v152, v151 offset:512
	ds_read_b32 v151, v154 offset:512
	ds_read_b32 v153, v153 offset:512
	v_add_u32_e32 v156, 0xffffff6f, v0
	v_max_i32_e32 v156, 0xffffff80, v156
	v_lshl_add_u32 v158, v156, 2, s68
	v_add_u32_e32 v156, 0xffffff70, v0
	v_add_u32_e32 v154, 0xffffff6e, v0
	v_add_u32_e32 v155, 0xffffff8e, v0
	v_add_u32_e32 v157, 0xffffff8f, v0
	v_add_u32_e32 v159, 0xffffff90, v0
	v_max_i32_e32 v156, 0xffffff80, v156
	v_add_u32_e32 v161, 0xffffff91, v0
	v_max_i32_e32 v154, 0xffffff80, v154
	v_max_i32_e32 v155, 0xffffff80, v155
	v_max_i32_e32 v157, 0xffffff80, v157
	v_max_i32_e32 v159, 0xffffff80, v159
	v_lshl_add_u32 v160, v156, 2, s68
	v_add_u32_e32 v156, 0xffffff71, v0
	v_max_i32_e32 v161, 0xffffff80, v161
	v_lshl_add_u32 v154, v154, 2, s68
	v_lshl_add_u32 v155, v155, 2, s68
	v_lshl_add_u32 v157, v157, 2, s68
	v_lshl_add_u32 v159, v159, 2, s68
	v_max_i32_e32 v156, 0xffffff80, v156
	v_lshl_add_u32 v161, v161, 2, s68
	v_lshl_add_u32 v162, v156, 2, s68
	ds_read_b32 v154, v154 offset:512
	ds_read_b32 v156, v155 offset:512
	ds_read_b32 v155, v158 offset:512
	ds_read_b32 v157, v157 offset:512
	ds_read_b32 v158, v160 offset:512
	ds_read_b32 v160, v159 offset:512
	ds_read_b32 v159, v162 offset:512
	ds_read_b32 v161, v161 offset:512
	v_add_u32_e32 v184, 0xffffff97, v0
	v_max_i32_e32 v184, 0xffffff80, v184
	v_lshl_add_u32 v185, v184, 2, s68
	v_add_u32_e32 v184, 0xffffff78, v0
	v_add_u32_e32 v186, 0xffffff98, v0
	v_max_i32_e32 v184, 0xffffff80, v184
	v_add_u32_e32 v162, 0xffffff76, v0
	v_add_u32_e32 v163, 0xffffff96, v0
	v_max_i32_e32 v186, 0xffffff80, v186
	v_lshl_add_u32 v187, v184, 2, s68
	v_add_u32_e32 v184, 0xffffff79, v0
	v_max_i32_e32 v162, 0xffffff80, v162
	v_max_i32_e32 v163, 0xffffff80, v163
	v_add_u32_e32 v183, 0xffffff77, v0
	v_lshl_add_u32 v188, v186, 2, s68
	v_add_u32_e32 v186, 0xffffff99, v0
	v_max_i32_e32 v184, 0xffffff80, v184
	v_lshl_add_u32 v162, v162, 2, s68
	v_lshl_add_u32 v163, v163, 2, s68
	v_max_i32_e32 v183, 0xffffff80, v183
	v_max_i32_e32 v186, 0xffffff80, v186
	v_lshl_add_u32 v189, v184, 2, s68
	v_lshl_add_u32 v183, v183, 2, s68
	v_lshl_add_u32 v190, v186, 2, s68
	ds_read_b32 v162, v162 offset:512
	ds_read_b32 v184, v163 offset:512
	ds_read_b32 v163, v183 offset:512
	ds_read_b32 v185, v185 offset:512
	ds_read_b32 v186, v187 offset:512
	ds_read_b32 v188, v188 offset:512
	ds_read_b32 v187, v189 offset:512
	ds_read_b32 v189, v190 offset:512
	v_add_u32_e32 v183, 0xffffff7e, v0
	v_add_u32_e32 v190, 0xffffff9e, v0
	v_max_i32_e32 v183, 0xffffff80, v183
	v_add_u32_e32 v191, 0xffffff7f, v0
	v_add_u32_e32 v192, 0xffffff9f, v0
	v_add_u32_e32 v193, 0xffffff80, v0
	v_add_u32_e32 v196, 0xffffffa0, v0
	v_add_u32_e32 v197, 0xffffff81, v0
	v_add_u32_e32 v0, 0xffffffa1, v0
	v_max_i32_e32 v190, 0xffffff80, v190
	v_lshl_add_u32 v183, v183, 2, s68
	v_max_i32_e32 v191, 0xffffff80, v191
	v_max_i32_e32 v192, 0xffffff80, v192
	v_max_i32_e32 v193, 0xffffff80, v193
	v_max_i32_e32 v196, 0xffffff80, v196
	v_max_i32_e32 v197, 0xffffff80, v197
	v_max_i32_e32 v0, 0xffffff80, v0
	v_lshl_add_u32 v190, v190, 2, s68
	v_lshl_add_u32 v191, v191, 2, s68
	v_lshl_add_u32 v192, v192, 2, s68
	v_lshl_add_u32 v193, v193, 2, s68
	v_lshl_add_u32 v196, v196, 2, s68
	v_lshl_add_u32 v197, v197, 2, s68
	s_waitcnt lgkmcnt(14)
	v_pk_add_f32 v[82:83], v[82:83], v[150:151]
	v_pk_add_f32 v[80:81], v[80:81], v[14:15]
	s_waitcnt lgkmcnt(9)
	v_pk_add_f32 v[86:87], v[86:87], v[158:159]
	v_pk_add_f32 v[84:85], v[84:85], v[154:155]
	v_lshl_add_u32 v0, v0, 2, s68
	ds_read_b32 v14, v183 offset:512
	ds_read_b32 v150, v190 offset:512
	ds_read_b32 v154, v193 offset:512
	ds_read_b32 v155, v197 offset:512
	ds_read_b32 v15, v191 offset:512
	ds_read_b32 v151, v192 offset:512
	ds_read_b32 v158, v196 offset:512
	ds_read_b32 v159, v0 offset:512
	s_waitcnt lgkmcnt(9)
	v_pk_add_f32 v[90:91], v[90:91], v[186:187]
	v_pk_add_f32 v[88:89], v[88:89], v[162:163]
	s_waitcnt lgkmcnt(4)
	v_pk_add_f32 v[94:95], v[94:95], v[154:155]
	s_waitcnt lgkmcnt(3)
	v_pk_add_f32 v[92:93], v[92:93], v[14:15]
	v_pk_add_f32 v[98:99], v[98:99], v[152:153]
	v_pk_add_f32 v[96:97], v[96:97], v[148:149]
	v_pk_add_f32 v[102:103], v[102:103], v[160:161]
	v_pk_add_f32 v[100:101], v[100:101], v[156:157]
	v_pk_add_f32 v[106:107], v[106:107], v[188:189]
	v_pk_add_f32 v[104:105], v[104:105], v[184:185]
	s_waitcnt lgkmcnt(0)
	v_pk_add_f32 v[110:111], v[110:111], v[158:159]
	v_pk_add_f32 v[108:109], v[108:109], v[150:151]

.Lqf_464:
	s_waitcnt vmcnt(4)
	v_perm_b32 v0, v6, v2, s100
	v_perm_b32 v2, v6, v2, s101
	ds_write2_b32 v178, v0, v2 offset1:34
	v_perm_b32 v0, v7, v3, s100
	v_perm_b32 v2, v7, v3, s101
	ds_write2_b32 v178, v0, v2 offset0:68 offset1:102
	v_perm_b32 v0, v8, v4, s100
	v_perm_b32 v2, v8, v4, s101
	s_add_i32 s44, s44, 2
	ds_write2_b32 v178, v0, v2 offset0:136 offset1:170
	v_perm_b32 v0, v9, v5, s100
	v_perm_b32 v2, v9, v5, s101
	s_addk_i32 s45, 0x80
	s_cmp_gt_i32 s44, s41
	ds_write2_b32 v178, v0, v2 offset0:204 offset1:238
	s_waitcnt lgkmcnt(0)
	s_barrier
	s_cselect_b64 s[20:21], -1, 0
	s_and_b64 vcc, exec, s[20:21]
	s_cbranch_vccz .Lqf_451
